# v8_attn
# speedup vs baseline: 1.0065x; 1.0025x over previous
; __device__ __forceinline__ u16 f2bf(float f) { return (u16)pack2(f, f); }
; __device__ void attn_item(const Params& P, int item, u16* shm, int wid_s) {
;     ...
;       for (int sbi = 0; sbi < 4; ++sbi) {
;         const int sb = 3 - sbi;
;         const int kpos_base = kb * 64 + sb * 16;
;         if (kpos_base >= qmax) {
; #pragma unroll
;           for (int j = 0; j < 4; ++j) Ps[(fq * 4 + j) * 72 + sb * 16 + fr] = 0;
;           continue;
;         }
;         f32x4 S = {0.f, 0.f, 0.f, 0.f};
; #pragma unroll
;         for (int kk = 0; kk < 4; ++kk) {
;           bf16x8 kf = *reinterpret_cast<const bf16x8*>(Ks + (sb * 16 + fr) * 136 + kk * 32 + fq * 8);
;           S = __builtin_amdgcn_mfma_f32_16x16x32_bf16(qf[kk], kf, S, 0, 0, 0);
;         }
;         const int kp = kpos_base + fr;
; #pragma unroll
;         for (int j = 0; j < 4; ++j) {
;           const int qp = qpos0 + r0 + fq * 4 + j;
;           const bool valid = kp < qp;
;           float z = S[j] * scale;
;           float sp = fmaxf(z, 0.f) + __logf(1.f + __expf(-fabsf(z)));
;           float l = valid ? -sp : 0.f;
;           float incl = l;
;           incl += dppf<0x101>(incl); incl += dppf<0x102>(incl); incl += dppf<0x104>(incl); incl += dppf<0x108>(incl);
;           float tail = carry[j] + incl - l;
;           float a = valid ? __expf(z + l + tail) : 0.f;
;           carry[j] += red16(l);
;           Ps[(fq * 4 + j) * 72 + sb * 16 + fr] = f2bf(a);
;         }
.LBB0_161:
	v_cmp_ngt_f32_e32 vcc, s18, v36
	v_cmp_ngt_f32_e64 s[6:7], s18, v37
	s_or_b64 s[8:9], vcc, s[6:7]
	v_cmp_ngt_f32_e32 vcc, s18, v38
	v_cmp_ngt_f32_e64 s[6:7], s18, v39
	s_or_b64 s[8:9], s[8:9], vcc
	s_or_b64 s[8:9], s[8:9], s[6:7]
	s_cmp_lg_u64 s[8:9], 0
	s_cselect_b64 s[8:9], -1, 0
	v_cmp_lt_i32_e32 vcc, s35, v86
	s_and_b64 s[6:7], s[0:1], vcc
	s_and_b64 s[6:7], s[6:7], s[8:9]
	s_and_saveexec_b64 s[20:21], s[6:7]
	s_cbranch_execz .LBB0_239
	s_add_i32 s6, s35, 48
	v_cmp_ge_u32_e64 s[8:9], s6, v86
	v_add_u32_e32 v2, s6, v84
	s_cmp_lg_u64 s[8:9], 0
	s_cbranch_scc1 .Latt_mask3
	ds_read_b128 v[130:133], v98 offset:13056
	ds_read_b128 v[134:137], v98 offset:13120
	ds_read_b128 v[138:141], v98 offset:13184
	ds_read_b128 v[142:145], v98 offset:13248
	s_waitcnt lgkmcnt(3)
	v_mfma_f32_16x16x32_bf16 v[72:75], v[4:7], v[130:133], 0
	s_waitcnt lgkmcnt(2)
	v_mfma_f32_16x16x32_bf16 v[72:75], v[8:11], v[134:137], v[72:75]
	s_waitcnt lgkmcnt(1)
	v_mfma_f32_16x16x32_bf16 v[72:75], v[12:15], v[138:141], v[72:75]
	s_waitcnt lgkmcnt(0)
	v_mfma_f32_16x16x32_bf16 v[72:75], v[16:19], v[142:145], v[72:75]
	v_cmp_lt_i32_e32 vcc, v2, v89
	v_cmp_le_i32_e64 s[8:9], v2, v89
	v_cmp_lt_i32_e64 s[26:27], v2, v91
	v_cmp_lt_i32_e64 s[6:7], v2, v92
	s_nop 3
	v_mul_f32_e32 v72, 0x3db504f3, v72
	v_mul_f32_e32 v73, 0x3db504f3, v73
	v_mul_f32_e32 v74, 0x3db504f3, v74
	v_mul_f32_e32 v75, 0x3db504f3, v75
	v_mul_f32_e64 v100, |v72|, s77
	v_mul_f32_e64 v101, |v73|, s77
	v_mul_f32_e64 v102, |v74|, s77
	v_mul_f32_e64 v103, |v75|, s77
	v_exp_f32_e32 v100, v100
	v_exp_f32_e32 v101, v101
	v_exp_f32_e32 v102, v102
	v_exp_f32_e32 v103, v103
	v_max_f32_e32 v114, 0, v72
	v_max_f32_e32 v115, 0, v73
	v_max_f32_e32 v116, 0, v74
	v_max_f32_e32 v117, 0, v75
	v_add_f32_e32 v100, 1.0, v100
	v_add_f32_e32 v101, 1.0, v101
	v_add_f32_e32 v102, 1.0, v102
	v_add_f32_e32 v103, 1.0, v103
	v_log_f32_e32 v100, v100
	v_log_f32_e32 v101, v101
	v_log_f32_e32 v102, v102
	v_log_f32_e32 v103, v103
	s_nop 0
	v_fmamk_f32 v104, v100, 0x3f317217, v114
	v_fmamk_f32 v105, v101, 0x3f317217, v115
	v_fmamk_f32 v106, v102, 0x3f317217, v116
	v_fmamk_f32 v107, v103, 0x3f317217, v117
	v_cndmask_b32_e64 v104, 0, -v104, vcc
	v_cndmask_b32_e64 v105, 0, -v105, s[8:9]
	v_cndmask_b32_e64 v106, 0, -v106, s[26:27]
	v_cndmask_b32_e64 v107, 0, -v107, s[6:7]
	v_add_f32_dpp v108, v104, v104 row_shl:1 row_mask:0xf bank_mask:0xf bound_ctrl:1
	v_add_f32_dpp v109, v105, v105 row_shl:1 row_mask:0xf bank_mask:0xf bound_ctrl:1
	v_add_f32_dpp v110, v106, v106 row_shl:1 row_mask:0xf bank_mask:0xf bound_ctrl:1
	v_add_f32_dpp v111, v107, v107 row_shl:1 row_mask:0xf bank_mask:0xf bound_ctrl:1
	v_add_f32_dpp v122, v104, v104 quad_perm:[1,0,3,2] row_mask:0xf bank_mask:0xf bound_ctrl:1
	v_add_f32_dpp v123, v105, v105 quad_perm:[1,0,3,2] row_mask:0xf bank_mask:0xf bound_ctrl:1
	v_add_f32_dpp v124, v106, v106 quad_perm:[1,0,3,2] row_mask:0xf bank_mask:0xf bound_ctrl:1
	v_add_f32_dpp v125, v107, v107 quad_perm:[1,0,3,2] row_mask:0xf bank_mask:0xf bound_ctrl:1
	v_add_f32_dpp v108, v108, v108 row_shl:2 row_mask:0xf bank_mask:0xf bound_ctrl:1
	v_add_f32_dpp v109, v109, v109 row_shl:2 row_mask:0xf bank_mask:0xf bound_ctrl:1
	v_add_f32_dpp v110, v110, v110 row_shl:2 row_mask:0xf bank_mask:0xf bound_ctrl:1
	v_add_f32_dpp v111, v111, v111 row_shl:2 row_mask:0xf bank_mask:0xf bound_ctrl:1
	v_add_f32_dpp v122, v122, v122 quad_perm:[2,3,0,1] row_mask:0xf bank_mask:0xf bound_ctrl:1
	v_add_f32_dpp v123, v123, v123 quad_perm:[2,3,0,1] row_mask:0xf bank_mask:0xf bound_ctrl:1
	v_add_f32_dpp v124, v124, v124 quad_perm:[2,3,0,1] row_mask:0xf bank_mask:0xf bound_ctrl:1
	v_add_f32_dpp v125, v125, v125 quad_perm:[2,3,0,1] row_mask:0xf bank_mask:0xf bound_ctrl:1
	v_add_f32_dpp v108, v108, v108 row_shl:4 row_mask:0xf bank_mask:0xf bound_ctrl:1
	v_add_f32_dpp v109, v109, v109 row_shl:4 row_mask:0xf bank_mask:0xf bound_ctrl:1
	v_add_f32_dpp v110, v110, v110 row_shl:4 row_mask:0xf bank_mask:0xf bound_ctrl:1
	v_add_f32_dpp v111, v111, v111 row_shl:4 row_mask:0xf bank_mask:0xf bound_ctrl:1
	v_add_f32_dpp v122, v122, v122 row_ror:4 row_mask:0xf bank_mask:0xf bound_ctrl:1
	v_add_f32_dpp v123, v123, v123 row_ror:4 row_mask:0xf bank_mask:0xf bound_ctrl:1
	v_add_f32_dpp v124, v124, v124 row_ror:4 row_mask:0xf bank_mask:0xf bound_ctrl:1
	v_add_f32_dpp v125, v125, v125 row_ror:4 row_mask:0xf bank_mask:0xf bound_ctrl:1
	v_mov_b32_dpp v118, v108 row_shl:8 row_mask:0xf bank_mask:0xf bound_ctrl:1
	v_mov_b32_dpp v119, v109 row_shl:8 row_mask:0xf bank_mask:0xf bound_ctrl:1
	v_mov_b32_dpp v120, v110 row_shl:8 row_mask:0xf bank_mask:0xf bound_ctrl:1
	v_mov_b32_dpp v121, v111 row_shl:8 row_mask:0xf bank_mask:0xf bound_ctrl:1
	v_add_f32_dpp v122, v122, v122 row_ror:8 row_mask:0xf bank_mask:0xf bound_ctrl:1
	v_add_f32_dpp v123, v123, v123 row_ror:8 row_mask:0xf bank_mask:0xf bound_ctrl:1
	v_add_f32_dpp v124, v124, v124 row_ror:8 row_mask:0xf bank_mask:0xf bound_ctrl:1
	v_add_f32_dpp v125, v125, v125 row_ror:8 row_mask:0xf bank_mask:0xf bound_ctrl:1
	v_add_f32_e32 v108, v108, v118
	v_add_f32_e32 v109, v109, v119
	v_add_f32_e32 v110, v110, v120
	v_add_f32_e32 v111, v111, v121
	v_add_f32_e32 v108, v36, v108
	v_add_f32_e32 v109, v37, v109
	v_add_f32_e32 v110, v38, v110
	v_add_f32_e32 v111, v39, v111
	v_add_f32_e32 v108, v72, v108
	v_add_f32_e32 v109, v73, v109
	v_add_f32_e32 v110, v74, v110
	v_add_f32_e32 v111, v75, v111
	v_add_f32_e32 v36, v36, v122
	v_add_f32_e32 v37, v37, v123
	v_add_f32_e32 v38, v38, v124
	v_add_f32_e32 v39, v39, v125
	v_mul_f32_e32 v108, 0x3fb8aa3b, v108
	v_mul_f32_e32 v109, 0x3fb8aa3b, v109
	v_mul_f32_e32 v110, 0x3fb8aa3b, v110
	v_mul_f32_e32 v111, 0x3fb8aa3b, v111
	v_exp_f32_e32 v108, v108
	v_exp_f32_e32 v109, v109
	v_exp_f32_e32 v110, v110
	v_exp_f32_e32 v111, v111
	s_nop 0
	v_cndmask_b32_e64 v108, 0, v108, vcc
	v_cndmask_b32_e64 v109, 0, v109, s[8:9]
	v_cndmask_b32_e64 v110, 0, v110, s[26:27]
	v_cndmask_b32_e64 v111, 0, v111, s[6:7]
	v_cvt_pk_bf16_f32 v108, v108, v108
	v_cvt_pk_bf16_f32 v109, v109, v109
	v_cvt_pk_bf16_f32 v110, v110, v110
	v_cvt_pk_bf16_f32 v111, v111, v111
	ds_write_b16 v97, v108 offset:35936
	ds_write_b16 v97, v109 offset:36080
	ds_write_b16 v97, v110 offset:36224
	ds_write_b16 v97, v111 offset:36368
	s_branch .Latt_next3
; __device__ __forceinline__ u16 f2bf(float f) { return (u16)pack2(f, f); }
; __device__ void attn_item(const Params& P, int item, u16* shm, int wid_s) {
;     ...
;       for (int sbi = 0; sbi < 4; ++sbi) {
;         const int sb = 3 - sbi;
;         const int kpos_base = kb * 64 + sb * 16;
;         if (kpos_base >= qmax) {
; #pragma unroll
;           for (int j = 0; j < 4; ++j) Ps[(fq * 4 + j) * 72 + sb * 16 + fr] = 0;
;           continue;
;         }
;         f32x4 S = {0.f, 0.f, 0.f, 0.f};
; #pragma unroll
;         for (int kk = 0; kk < 4; ++kk) {
;           bf16x8 kf = *reinterpret_cast<const bf16x8*>(Ks + (sb * 16 + fr) * 136 + kk * 32 + fq * 8);
;           S = __builtin_amdgcn_mfma_f32_16x16x32_bf16(qf[kk], kf, S, 0, 0, 0);
;         }
;         const int kp = kpos_base + fr;
; #pragma unroll
;         for (int j = 0; j < 4; ++j) {
;           const int qp = qpos0 + r0 + fq * 4 + j;
;           const bool valid = kp < qp;
;           float z = S[j] * scale;
;           float sp = fmaxf(z, 0.f) + __logf(1.f + __expf(-fabsf(z)));
;           float l = valid ? -sp : 0.f;
;           float incl = l;
;           incl += dppf<0x101>(incl); incl += dppf<0x102>(incl); incl += dppf<0x104>(incl); incl += dppf<0x108>(incl);
;           float tail = carry[j] + incl - l;
;           float a = valid ? __expf(z + l + tail) : 0.f;
;           carry[j] += red16(l);
;           Ps[(fq * 4 + j) * 72 + sb * 16 + fr] = f2bf(a);
;         }
.Latt_mask3:
	ds_write_b16 v97, v1 offset:35936
	ds_write_b16 v97, v1 offset:36080
	ds_write_b16 v97, v1 offset:36224
	ds_write_b16 v97, v1 offset:36368
.Latt_next3:
	s_add_i32 s6, s35, 32
	v_cmp_ge_u32_e64 s[8:9], s6, v86
	v_add_u32_e32 v2, s6, v84
	s_cmp_lg_u64 s[8:9], 0
	s_cbranch_scc1 .Latt_mask2
	ds_read_b128 v[130:133], v98 offset:8704
	ds_read_b128 v[134:137], v98 offset:8768
	ds_read_b128 v[138:141], v98 offset:8832
	ds_read_b128 v[142:145], v98 offset:8896
	s_waitcnt lgkmcnt(3)
	v_mfma_f32_16x16x32_bf16 v[72:75], v[4:7], v[130:133], 0
	s_waitcnt lgkmcnt(2)
	v_mfma_f32_16x16x32_bf16 v[72:75], v[8:11], v[134:137], v[72:75]
	s_waitcnt lgkmcnt(1)
	v_mfma_f32_16x16x32_bf16 v[72:75], v[12:15], v[138:141], v[72:75]
	s_waitcnt lgkmcnt(0)
	v_mfma_f32_16x16x32_bf16 v[72:75], v[16:19], v[142:145], v[72:75]
	v_cmp_lt_i32_e32 vcc, v2, v89
	v_cmp_le_i32_e64 s[8:9], v2, v89
	v_cmp_lt_i32_e64 s[26:27], v2, v91
	v_cmp_lt_i32_e64 s[6:7], v2, v92
	s_nop 3
	v_mul_f32_e32 v72, 0x3db504f3, v72
	v_mul_f32_e32 v73, 0x3db504f3, v73
	v_mul_f32_e32 v74, 0x3db504f3, v74
	v_mul_f32_e32 v75, 0x3db504f3, v75
	v_mul_f32_e64 v100, |v72|, s77
	v_mul_f32_e64 v101, |v73|, s77
	v_mul_f32_e64 v102, |v74|, s77
	v_mul_f32_e64 v103, |v75|, s77
	v_exp_f32_e32 v100, v100
	v_exp_f32_e32 v101, v101
	v_exp_f32_e32 v102, v102
	v_exp_f32_e32 v103, v103
	v_max_f32_e32 v114, 0, v72
	v_max_f32_e32 v115, 0, v73
	v_max_f32_e32 v116, 0, v74
	v_max_f32_e32 v117, 0, v75
	v_add_f32_e32 v100, 1.0, v100
	v_add_f32_e32 v101, 1.0, v101
	v_add_f32_e32 v102, 1.0, v102
	v_add_f32_e32 v103, 1.0, v103
	v_log_f32_e32 v100, v100
	v_log_f32_e32 v101, v101
	v_log_f32_e32 v102, v102
	v_log_f32_e32 v103, v103
	s_nop 0
	v_fmamk_f32 v104, v100, 0x3f317217, v114
	v_fmamk_f32 v105, v101, 0x3f317217, v115
	v_fmamk_f32 v106, v102, 0x3f317217, v116
	v_fmamk_f32 v107, v103, 0x3f317217, v117
	v_cndmask_b32_e64 v104, 0, -v104, vcc
	v_cndmask_b32_e64 v105, 0, -v105, s[8:9]
	v_cndmask_b32_e64 v106, 0, -v106, s[26:27]
	v_cndmask_b32_e64 v107, 0, -v107, s[6:7]
	v_add_f32_dpp v108, v104, v104 row_shl:1 row_mask:0xf bank_mask:0xf bound_ctrl:1
	v_add_f32_dpp v109, v105, v105 row_shl:1 row_mask:0xf bank_mask:0xf bound_ctrl:1
	v_add_f32_dpp v110, v106, v106 row_shl:1 row_mask:0xf bank_mask:0xf bound_ctrl:1
	v_add_f32_dpp v111, v107, v107 row_shl:1 row_mask:0xf bank_mask:0xf bound_ctrl:1
	v_add_f32_dpp v122, v104, v104 quad_perm:[1,0,3,2] row_mask:0xf bank_mask:0xf bound_ctrl:1
	v_add_f32_dpp v123, v105, v105 quad_perm:[1,0,3,2] row_mask:0xf bank_mask:0xf bound_ctrl:1
	v_add_f32_dpp v124, v106, v106 quad_perm:[1,0,3,2] row_mask:0xf bank_mask:0xf bound_ctrl:1
	v_add_f32_dpp v125, v107, v107 quad_perm:[1,0,3,2] row_mask:0xf bank_mask:0xf bound_ctrl:1
	v_add_f32_dpp v108, v108, v108 row_shl:2 row_mask:0xf bank_mask:0xf bound_ctrl:1
	v_add_f32_dpp v109, v109, v109 row_shl:2 row_mask:0xf bank_mask:0xf bound_ctrl:1
	v_add_f32_dpp v110, v110, v110 row_shl:2 row_mask:0xf bank_mask:0xf bound_ctrl:1
	v_add_f32_dpp v111, v111, v111 row_shl:2 row_mask:0xf bank_mask:0xf bound_ctrl:1
	v_add_f32_dpp v122, v122, v122 quad_perm:[2,3,0,1] row_mask:0xf bank_mask:0xf bound_ctrl:1
	v_add_f32_dpp v123, v123, v123 quad_perm:[2,3,0,1] row_mask:0xf bank_mask:0xf bound_ctrl:1
	v_add_f32_dpp v124, v124, v124 quad_perm:[2,3,0,1] row_mask:0xf bank_mask:0xf bound_ctrl:1
	v_add_f32_dpp v125, v125, v125 quad_perm:[2,3,0,1] row_mask:0xf bank_mask:0xf bound_ctrl:1
	v_add_f32_dpp v108, v108, v108 row_shl:4 row_mask:0xf bank_mask:0xf bound_ctrl:1
	v_add_f32_dpp v109, v109, v109 row_shl:4 row_mask:0xf bank_mask:0xf bound_ctrl:1
	v_add_f32_dpp v110, v110, v110 row_shl:4 row_mask:0xf bank_mask:0xf bound_ctrl:1
	v_add_f32_dpp v111, v111, v111 row_shl:4 row_mask:0xf bank_mask:0xf bound_ctrl:1
	v_add_f32_dpp v122, v122, v122 row_ror:4 row_mask:0xf bank_mask:0xf bound_ctrl:1
	v_add_f32_dpp v123, v123, v123 row_ror:4 row_mask:0xf bank_mask:0xf bound_ctrl:1
	v_add_f32_dpp v124, v124, v124 row_ror:4 row_mask:0xf bank_mask:0xf bound_ctrl:1
	v_add_f32_dpp v125, v125, v125 row_ror:4 row_mask:0xf bank_mask:0xf bound_ctrl:1
	v_mov_b32_dpp v118, v108 row_shl:8 row_mask:0xf bank_mask:0xf bound_ctrl:1
	v_mov_b32_dpp v119, v109 row_shl:8 row_mask:0xf bank_mask:0xf bound_ctrl:1
	v_mov_b32_dpp v120, v110 row_shl:8 row_mask:0xf bank_mask:0xf bound_ctrl:1
	v_mov_b32_dpp v121, v111 row_shl:8 row_mask:0xf bank_mask:0xf bound_ctrl:1
	v_add_f32_dpp v122, v122, v122 row_ror:8 row_mask:0xf bank_mask:0xf bound_ctrl:1
	v_add_f32_dpp v123, v123, v123 row_ror:8 row_mask:0xf bank_mask:0xf bound_ctrl:1
	v_add_f32_dpp v124, v124, v124 row_ror:8 row_mask:0xf bank_mask:0xf bound_ctrl:1
	v_add_f32_dpp v125, v125, v125 row_ror:8 row_mask:0xf bank_mask:0xf bound_ctrl:1
	v_add_f32_e32 v108, v108, v118
	v_add_f32_e32 v109, v109, v119
	v_add_f32_e32 v110, v110, v120
	v_add_f32_e32 v111, v111, v121
	v_add_f32_e32 v108, v36, v108
	v_add_f32_e32 v109, v37, v109
	v_add_f32_e32 v110, v38, v110
	v_add_f32_e32 v111, v39, v111
	v_add_f32_e32 v108, v72, v108
	v_add_f32_e32 v109, v73, v109
	v_add_f32_e32 v110, v74, v110
	v_add_f32_e32 v111, v75, v111
	v_add_f32_e32 v36, v36, v122
	v_add_f32_e32 v37, v37, v123
	v_add_f32_e32 v38, v38, v124
	v_add_f32_e32 v39, v39, v125
	v_mul_f32_e32 v108, 0x3fb8aa3b, v108
	v_mul_f32_e32 v109, 0x3fb8aa3b, v109
	v_mul_f32_e32 v110, 0x3fb8aa3b, v110
	v_mul_f32_e32 v111, 0x3fb8aa3b, v111
	v_exp_f32_e32 v108, v108
	v_exp_f32_e32 v109, v109
	v_exp_f32_e32 v110, v110
	v_exp_f32_e32 v111, v111
	s_nop 0
	v_cndmask_b32_e64 v108, 0, v108, vcc
	v_cndmask_b32_e64 v109, 0, v109, s[8:9]
	v_cndmask_b32_e64 v110, 0, v110, s[26:27]
	v_cndmask_b32_e64 v111, 0, v111, s[6:7]
	v_cvt_pk_bf16_f32 v108, v108, v108
	v_cvt_pk_bf16_f32 v109, v109, v109
	v_cvt_pk_bf16_f32 v110, v110, v110
	v_cvt_pk_bf16_f32 v111, v111, v111
	ds_write_b16 v97, v108 offset:35904
	ds_write_b16 v97, v109 offset:36048
	ds_write_b16 v97, v110 offset:36192
	ds_write_b16 v97, v111 offset:36336
	s_branch .Latt_next2
; __device__ __forceinline__ u16 f2bf(float f) { return (u16)pack2(f, f); }
; __device__ void attn_item(const Params& P, int item, u16* shm, int wid_s) {
;     ...
;       for (int sbi = 0; sbi < 4; ++sbi) {
;         const int sb = 3 - sbi;
;         const int kpos_base = kb * 64 + sb * 16;
;         if (kpos_base >= qmax) {
; #pragma unroll
;           for (int j = 0; j < 4; ++j) Ps[(fq * 4 + j) * 72 + sb * 16 + fr] = 0;
;           continue;
;         }
;         f32x4 S = {0.f, 0.f, 0.f, 0.f};
; #pragma unroll
;         for (int kk = 0; kk < 4; ++kk) {
;           bf16x8 kf = *reinterpret_cast<const bf16x8*>(Ks + (sb * 16 + fr) * 136 + kk * 32 + fq * 8);
;           S = __builtin_amdgcn_mfma_f32_16x16x32_bf16(qf[kk], kf, S, 0, 0, 0);
;         }
;         const int kp = kpos_base + fr;
; #pragma unroll
;         for (int j = 0; j < 4; ++j) {
;           const int qp = qpos0 + r0 + fq * 4 + j;
;           const bool valid = kp < qp;
;           float z = S[j] * scale;
;           float sp = fmaxf(z, 0.f) + __logf(1.f + __expf(-fabsf(z)));
;           float l = valid ? -sp : 0.f;
;           float incl = l;
;           incl += dppf<0x101>(incl); incl += dppf<0x102>(incl); incl += dppf<0x104>(incl); incl += dppf<0x108>(incl);
;           float tail = carry[j] + incl - l;
;           float a = valid ? __expf(z + l + tail) : 0.f;
;           carry[j] += red16(l);
;           Ps[(fq * 4 + j) * 72 + sb * 16 + fr] = f2bf(a);
;         }
.Latt_mask2:
	ds_write_b16 v97, v1 offset:35904
	ds_write_b16 v97, v1 offset:36048
	ds_write_b16 v97, v1 offset:36192
	ds_write_b16 v97, v1 offset:36336
.Latt_next2:
	s_add_i32 s6, s35, 16
	v_cmp_ge_u32_e64 s[8:9], s6, v86
	v_add_u32_e32 v2, s6, v84
	s_cmp_lg_u64 s[8:9], 0
	s_cbranch_scc1 .Latt_mask1
	ds_read_b128 v[130:133], v98 offset:4352
	ds_read_b128 v[134:137], v98 offset:4416
	ds_read_b128 v[138:141], v98 offset:4480
	ds_read_b128 v[142:145], v98 offset:4544
	s_waitcnt lgkmcnt(3)
	v_mfma_f32_16x16x32_bf16 v[72:75], v[4:7], v[130:133], 0
	s_waitcnt lgkmcnt(2)
	v_mfma_f32_16x16x32_bf16 v[72:75], v[8:11], v[134:137], v[72:75]
	s_waitcnt lgkmcnt(1)
	v_mfma_f32_16x16x32_bf16 v[72:75], v[12:15], v[138:141], v[72:75]
	s_waitcnt lgkmcnt(0)
	v_mfma_f32_16x16x32_bf16 v[72:75], v[16:19], v[142:145], v[72:75]
	v_cmp_lt_i32_e32 vcc, v2, v89
	v_cmp_le_i32_e64 s[8:9], v2, v89
	v_cmp_lt_i32_e64 s[26:27], v2, v91
	v_cmp_lt_i32_e64 s[6:7], v2, v92
	s_nop 3
	v_mul_f32_e32 v72, 0x3db504f3, v72
	v_mul_f32_e32 v73, 0x3db504f3, v73
	v_mul_f32_e32 v74, 0x3db504f3, v74
	v_mul_f32_e32 v75, 0x3db504f3, v75
	v_mul_f32_e64 v100, |v72|, s77
	v_mul_f32_e64 v101, |v73|, s77
	v_mul_f32_e64 v102, |v74|, s77
	v_mul_f32_e64 v103, |v75|, s77
	v_exp_f32_e32 v100, v100
	v_exp_f32_e32 v101, v101
	v_exp_f32_e32 v102, v102
	v_exp_f32_e32 v103, v103
	v_max_f32_e32 v114, 0, v72
	v_max_f32_e32 v115, 0, v73
	v_max_f32_e32 v116, 0, v74
	v_max_f32_e32 v117, 0, v75
	v_add_f32_e32 v100, 1.0, v100
	v_add_f32_e32 v101, 1.0, v101
	v_add_f32_e32 v102, 1.0, v102
	v_add_f32_e32 v103, 1.0, v103
	v_log_f32_e32 v100, v100
	v_log_f32_e32 v101, v101
	v_log_f32_e32 v102, v102
	v_log_f32_e32 v103, v103
	s_nop 0
	v_fmamk_f32 v104, v100, 0x3f317217, v114
	v_fmamk_f32 v105, v101, 0x3f317217, v115
	v_fmamk_f32 v106, v102, 0x3f317217, v116
	v_fmamk_f32 v107, v103, 0x3f317217, v117
	v_cndmask_b32_e64 v104, 0, -v104, vcc
	v_cndmask_b32_e64 v105, 0, -v105, s[8:9]
	v_cndmask_b32_e64 v106, 0, -v106, s[26:27]
	v_cndmask_b32_e64 v107, 0, -v107, s[6:7]
	v_add_f32_dpp v108, v104, v104 row_shl:1 row_mask:0xf bank_mask:0xf bound_ctrl:1
	v_add_f32_dpp v109, v105, v105 row_shl:1 row_mask:0xf bank_mask:0xf bound_ctrl:1
	v_add_f32_dpp v110, v106, v106 row_shl:1 row_mask:0xf bank_mask:0xf bound_ctrl:1
	v_add_f32_dpp v111, v107, v107 row_shl:1 row_mask:0xf bank_mask:0xf bound_ctrl:1
	v_add_f32_dpp v122, v104, v104 quad_perm:[1,0,3,2] row_mask:0xf bank_mask:0xf bound_ctrl:1
	v_add_f32_dpp v123, v105, v105 quad_perm:[1,0,3,2] row_mask:0xf bank_mask:0xf bound_ctrl:1
	v_add_f32_dpp v124, v106, v106 quad_perm:[1,0,3,2] row_mask:0xf bank_mask:0xf bound_ctrl:1
	v_add_f32_dpp v125, v107, v107 quad_perm:[1,0,3,2] row_mask:0xf bank_mask:0xf bound_ctrl:1
	v_add_f32_dpp v108, v108, v108 row_shl:2 row_mask:0xf bank_mask:0xf bound_ctrl:1
	v_add_f32_dpp v109, v109, v109 row_shl:2 row_mask:0xf bank_mask:0xf bound_ctrl:1
	v_add_f32_dpp v110, v110, v110 row_shl:2 row_mask:0xf bank_mask:0xf bound_ctrl:1
	v_add_f32_dpp v111, v111, v111 row_shl:2 row_mask:0xf bank_mask:0xf bound_ctrl:1
	v_add_f32_dpp v122, v122, v122 quad_perm:[2,3,0,1] row_mask:0xf bank_mask:0xf bound_ctrl:1
	v_add_f32_dpp v123, v123, v123 quad_perm:[2,3,0,1] row_mask:0xf bank_mask:0xf bound_ctrl:1
	v_add_f32_dpp v124, v124, v124 quad_perm:[2,3,0,1] row_mask:0xf bank_mask:0xf bound_ctrl:1
	v_add_f32_dpp v125, v125, v125 quad_perm:[2,3,0,1] row_mask:0xf bank_mask:0xf bound_ctrl:1
	v_add_f32_dpp v108, v108, v108 row_shl:4 row_mask:0xf bank_mask:0xf bound_ctrl:1
	v_add_f32_dpp v109, v109, v109 row_shl:4 row_mask:0xf bank_mask:0xf bound_ctrl:1
	v_add_f32_dpp v110, v110, v110 row_shl:4 row_mask:0xf bank_mask:0xf bound_ctrl:1
	v_add_f32_dpp v111, v111, v111 row_shl:4 row_mask:0xf bank_mask:0xf bound_ctrl:1
	v_add_f32_dpp v122, v122, v122 row_ror:4 row_mask:0xf bank_mask:0xf bound_ctrl:1
	v_add_f32_dpp v123, v123, v123 row_ror:4 row_mask:0xf bank_mask:0xf bound_ctrl:1
	v_add_f32_dpp v124, v124, v124 row_ror:4 row_mask:0xf bank_mask:0xf bound_ctrl:1
	v_add_f32_dpp v125, v125, v125 row_ror:4 row_mask:0xf bank_mask:0xf bound_ctrl:1
	v_mov_b32_dpp v118, v108 row_shl:8 row_mask:0xf bank_mask:0xf bound_ctrl:1
	v_mov_b32_dpp v119, v109 row_shl:8 row_mask:0xf bank_mask:0xf bound_ctrl:1
	v_mov_b32_dpp v120, v110 row_shl:8 row_mask:0xf bank_mask:0xf bound_ctrl:1
	v_mov_b32_dpp v121, v111 row_shl:8 row_mask:0xf bank_mask:0xf bound_ctrl:1
	v_add_f32_dpp v122, v122, v122 row_ror:8 row_mask:0xf bank_mask:0xf bound_ctrl:1
	v_add_f32_dpp v123, v123, v123 row_ror:8 row_mask:0xf bank_mask:0xf bound_ctrl:1
	v_add_f32_dpp v124, v124, v124 row_ror:8 row_mask:0xf bank_mask:0xf bound_ctrl:1
	v_add_f32_dpp v125, v125, v125 row_ror:8 row_mask:0xf bank_mask:0xf bound_ctrl:1
	v_add_f32_e32 v108, v108, v118
	v_add_f32_e32 v109, v109, v119
	v_add_f32_e32 v110, v110, v120
	v_add_f32_e32 v111, v111, v121
	v_add_f32_e32 v108, v36, v108
	v_add_f32_e32 v109, v37, v109
	v_add_f32_e32 v110, v38, v110
	v_add_f32_e32 v111, v39, v111
	v_add_f32_e32 v108, v72, v108
	v_add_f32_e32 v109, v73, v109
	v_add_f32_e32 v110, v74, v110
	v_add_f32_e32 v111, v75, v111
	v_add_f32_e32 v36, v36, v122
	v_add_f32_e32 v37, v37, v123
	v_add_f32_e32 v38, v38, v124
	v_add_f32_e32 v39, v39, v125
	v_mul_f32_e32 v108, 0x3fb8aa3b, v108
	v_mul_f32_e32 v109, 0x3fb8aa3b, v109
	v_mul_f32_e32 v110, 0x3fb8aa3b, v110
	v_mul_f32_e32 v111, 0x3fb8aa3b, v111
	v_exp_f32_e32 v108, v108
	v_exp_f32_e32 v109, v109
	v_exp_f32_e32 v110, v110
	v_exp_f32_e32 v111, v111
	s_nop 0
	v_cndmask_b32_e64 v108, 0, v108, vcc
	v_cndmask_b32_e64 v109, 0, v109, s[8:9]
	v_cndmask_b32_e64 v110, 0, v110, s[26:27]
	v_cndmask_b32_e64 v111, 0, v111, s[6:7]
	v_cvt_pk_bf16_f32 v108, v108, v108
	v_cvt_pk_bf16_f32 v109, v109, v109
	v_cvt_pk_bf16_f32 v110, v110, v110
	v_cvt_pk_bf16_f32 v111, v111, v111
	ds_write_b16 v97, v108 offset:35872
	ds_write_b16 v97, v109 offset:36016
	ds_write_b16 v97, v110 offset:36160
	ds_write_b16 v97, v111 offset:36304
	s_branch .Latt_next1
; __device__ __forceinline__ u16 f2bf(float f) { return (u16)pack2(f, f); }
; __device__ void attn_item(const Params& P, int item, u16* shm, int wid_s) {
;     ...
;       for (int sbi = 0; sbi < 4; ++sbi) {
;         const int sb = 3 - sbi;
;         const int kpos_base = kb * 64 + sb * 16;
;         if (kpos_base >= qmax) {
; #pragma unroll
;           for (int j = 0; j < 4; ++j) Ps[(fq * 4 + j) * 72 + sb * 16 + fr] = 0;
;           continue;
;         }
;         f32x4 S = {0.f, 0.f, 0.f, 0.f};
; #pragma unroll
;         for (int kk = 0; kk < 4; ++kk) {
;           bf16x8 kf = *reinterpret_cast<const bf16x8*>(Ks + (sb * 16 + fr) * 136 + kk * 32 + fq * 8);
;           S = __builtin_amdgcn_mfma_f32_16x16x32_bf16(qf[kk], kf, S, 0, 0, 0);
;         }
;         const int kp = kpos_base + fr;
; #pragma unroll
;         for (int j = 0; j < 4; ++j) {
;           const int qp = qpos0 + r0 + fq * 4 + j;
;           const bool valid = kp < qp;
;           float z = S[j] * scale;
;           float sp = fmaxf(z, 0.f) + __logf(1.f + __expf(-fabsf(z)));
;           float l = valid ? -sp : 0.f;
;           float incl = l;
;           incl += dppf<0x101>(incl); incl += dppf<0x102>(incl); incl += dppf<0x104>(incl); incl += dppf<0x108>(incl);
;           float tail = carry[j] + incl - l;
;           float a = valid ? __expf(z + l + tail) : 0.f;
;           carry[j] += red16(l);
;           Ps[(fq * 4 + j) * 72 + sb * 16 + fr] = f2bf(a);
;         }
.Latt_mask1:
	ds_write_b16 v97, v1 offset:35872
	ds_write_b16 v97, v1 offset:36016
	ds_write_b16 v97, v1 offset:36160
	ds_write_b16 v97, v1 offset:36304
.Latt_next1:
	s_mov_b32 s6, s35
	v_cmp_ge_u32_e64 s[8:9], s6, v86
	v_add_u32_e32 v2, s6, v84
	s_cmp_lg_u64 s[8:9], 0
	s_cbranch_scc1 .Latt_mask0
	ds_read_b128 v[130:133], v98 offset:0
	ds_read_b128 v[134:137], v98 offset:64
	ds_read_b128 v[138:141], v98 offset:128
	ds_read_b128 v[142:145], v98 offset:192
	s_waitcnt lgkmcnt(3)
	v_mfma_f32_16x16x32_bf16 v[72:75], v[4:7], v[130:133], 0
	s_waitcnt lgkmcnt(2)
	v_mfma_f32_16x16x32_bf16 v[72:75], v[8:11], v[134:137], v[72:75]
	s_waitcnt lgkmcnt(1)
	v_mfma_f32_16x16x32_bf16 v[72:75], v[12:15], v[138:141], v[72:75]
	s_waitcnt lgkmcnt(0)
	v_mfma_f32_16x16x32_bf16 v[72:75], v[16:19], v[142:145], v[72:75]
	v_cmp_lt_i32_e32 vcc, v2, v89
	v_cmp_le_i32_e64 s[8:9], v2, v89
	v_cmp_lt_i32_e64 s[26:27], v2, v91
	v_cmp_lt_i32_e64 s[6:7], v2, v92
	s_nop 3
	v_mul_f32_e32 v72, 0x3db504f3, v72
	v_mul_f32_e32 v73, 0x3db504f3, v73
	v_mul_f32_e32 v74, 0x3db504f3, v74
	v_mul_f32_e32 v75, 0x3db504f3, v75
	v_mul_f32_e64 v100, |v72|, s77
	v_mul_f32_e64 v101, |v73|, s77
	v_mul_f32_e64 v102, |v74|, s77
	v_mul_f32_e64 v103, |v75|, s77
	v_exp_f32_e32 v100, v100
	v_exp_f32_e32 v101, v101
	v_exp_f32_e32 v102, v102
	v_exp_f32_e32 v103, v103
	v_max_f32_e32 v114, 0, v72
	v_max_f32_e32 v115, 0, v73
	v_max_f32_e32 v116, 0, v74
	v_max_f32_e32 v117, 0, v75
	v_add_f32_e32 v100, 1.0, v100
	v_add_f32_e32 v101, 1.0, v101
	v_add_f32_e32 v102, 1.0, v102
	v_add_f32_e32 v103, 1.0, v103
	v_log_f32_e32 v100, v100
	v_log_f32_e32 v101, v101
	v_log_f32_e32 v102, v102
	v_log_f32_e32 v103, v103
	s_nop 0
	v_fmamk_f32 v104, v100, 0x3f317217, v114
	v_fmamk_f32 v105, v101, 0x3f317217, v115
	v_fmamk_f32 v106, v102, 0x3f317217, v116
	v_fmamk_f32 v107, v103, 0x3f317217, v117
	v_cndmask_b32_e64 v104, 0, -v104, vcc
	v_cndmask_b32_e64 v105, 0, -v105, s[8:9]
	v_cndmask_b32_e64 v106, 0, -v106, s[26:27]
	v_cndmask_b32_e64 v107, 0, -v107, s[6:7]
	v_add_f32_dpp v108, v104, v104 row_shl:1 row_mask:0xf bank_mask:0xf bound_ctrl:1
	v_add_f32_dpp v109, v105, v105 row_shl:1 row_mask:0xf bank_mask:0xf bound_ctrl:1
	v_add_f32_dpp v110, v106, v106 row_shl:1 row_mask:0xf bank_mask:0xf bound_ctrl:1
	v_add_f32_dpp v111, v107, v107 row_shl:1 row_mask:0xf bank_mask:0xf bound_ctrl:1
	v_add_f32_dpp v122, v104, v104 quad_perm:[1,0,3,2] row_mask:0xf bank_mask:0xf bound_ctrl:1
	v_add_f32_dpp v123, v105, v105 quad_perm:[1,0,3,2] row_mask:0xf bank_mask:0xf bound_ctrl:1
	v_add_f32_dpp v124, v106, v106 quad_perm:[1,0,3,2] row_mask:0xf bank_mask:0xf bound_ctrl:1
	v_add_f32_dpp v125, v107, v107 quad_perm:[1,0,3,2] row_mask:0xf bank_mask:0xf bound_ctrl:1
	v_add_f32_dpp v108, v108, v108 row_shl:2 row_mask:0xf bank_mask:0xf bound_ctrl:1
	v_add_f32_dpp v109, v109, v109 row_shl:2 row_mask:0xf bank_mask:0xf bound_ctrl:1
	v_add_f32_dpp v110, v110, v110 row_shl:2 row_mask:0xf bank_mask:0xf bound_ctrl:1
	v_add_f32_dpp v111, v111, v111 row_shl:2 row_mask:0xf bank_mask:0xf bound_ctrl:1
	v_add_f32_dpp v122, v122, v122 quad_perm:[2,3,0,1] row_mask:0xf bank_mask:0xf bound_ctrl:1
	v_add_f32_dpp v123, v123, v123 quad_perm:[2,3,0,1] row_mask:0xf bank_mask:0xf bound_ctrl:1
	v_add_f32_dpp v124, v124, v124 quad_perm:[2,3,0,1] row_mask:0xf bank_mask:0xf bound_ctrl:1
	v_add_f32_dpp v125, v125, v125 quad_perm:[2,3,0,1] row_mask:0xf bank_mask:0xf bound_ctrl:1
	v_add_f32_dpp v108, v108, v108 row_shl:4 row_mask:0xf bank_mask:0xf bound_ctrl:1
	v_add_f32_dpp v109, v109, v109 row_shl:4 row_mask:0xf bank_mask:0xf bound_ctrl:1
	v_add_f32_dpp v110, v110, v110 row_shl:4 row_mask:0xf bank_mask:0xf bound_ctrl:1
	v_add_f32_dpp v111, v111, v111 row_shl:4 row_mask:0xf bank_mask:0xf bound_ctrl:1
	v_add_f32_dpp v122, v122, v122 row_ror:4 row_mask:0xf bank_mask:0xf bound_ctrl:1
	v_add_f32_dpp v123, v123, v123 row_ror:4 row_mask:0xf bank_mask:0xf bound_ctrl:1
	v_add_f32_dpp v124, v124, v124 row_ror:4 row_mask:0xf bank_mask:0xf bound_ctrl:1
	v_add_f32_dpp v125, v125, v125 row_ror:4 row_mask:0xf bank_mask:0xf bound_ctrl:1
	v_mov_b32_dpp v118, v108 row_shl:8 row_mask:0xf bank_mask:0xf bound_ctrl:1
	v_mov_b32_dpp v119, v109 row_shl:8 row_mask:0xf bank_mask:0xf bound_ctrl:1
	v_mov_b32_dpp v120, v110 row_shl:8 row_mask:0xf bank_mask:0xf bound_ctrl:1
	v_mov_b32_dpp v121, v111 row_shl:8 row_mask:0xf bank_mask:0xf bound_ctrl:1
	v_add_f32_dpp v122, v122, v122 row_ror:8 row_mask:0xf bank_mask:0xf bound_ctrl:1
	v_add_f32_dpp v123, v123, v123 row_ror:8 row_mask:0xf bank_mask:0xf bound_ctrl:1
	v_add_f32_dpp v124, v124, v124 row_ror:8 row_mask:0xf bank_mask:0xf bound_ctrl:1
	v_add_f32_dpp v125, v125, v125 row_ror:8 row_mask:0xf bank_mask:0xf bound_ctrl:1
	v_add_f32_e32 v108, v108, v118
	v_add_f32_e32 v109, v109, v119
	v_add_f32_e32 v110, v110, v120
	v_add_f32_e32 v111, v111, v121
	v_add_f32_e32 v108, v36, v108
	v_add_f32_e32 v109, v37, v109
	v_add_f32_e32 v110, v38, v110
	v_add_f32_e32 v111, v39, v111
	v_add_f32_e32 v108, v72, v108
	v_add_f32_e32 v109, v73, v109
	v_add_f32_e32 v110, v74, v110
	v_add_f32_e32 v111, v75, v111
	v_add_f32_e32 v36, v36, v122
	v_add_f32_e32 v37, v37, v123
	v_add_f32_e32 v38, v38, v124
	v_add_f32_e32 v39, v39, v125
	v_mul_f32_e32 v108, 0x3fb8aa3b, v108
	v_mul_f32_e32 v109, 0x3fb8aa3b, v109
	v_mul_f32_e32 v110, 0x3fb8aa3b, v110
	v_mul_f32_e32 v111, 0x3fb8aa3b, v111
	v_exp_f32_e32 v108, v108
	v_exp_f32_e32 v109, v109
	v_exp_f32_e32 v110, v110
	v_exp_f32_e32 v111, v111
	s_nop 0
	v_cndmask_b32_e64 v108, 0, v108, vcc
	v_cndmask_b32_e64 v109, 0, v109, s[8:9]
	v_cndmask_b32_e64 v110, 0, v110, s[26:27]
	v_cndmask_b32_e64 v111, 0, v111, s[6:7]
	v_cvt_pk_bf16_f32 v108, v108, v108
	v_cvt_pk_bf16_f32 v109, v109, v109
	v_cvt_pk_bf16_f32 v110, v110, v110
	v_cvt_pk_bf16_f32 v111, v111, v111
	ds_write_b16 v97, v108 offset:35840
	ds_write_b16 v97, v109 offset:35984
	ds_write_b16 v97, v110 offset:36128
	ds_write_b16 v97, v111 offset:36272
	s_branch .Latt_next0
; __device__ void attn_item(const Params& P, int item, u16* shm, int wid_s) {
;     ...
;         if (kpos_base >= qmax) {
; #pragma unroll
;           for (int j = 0; j < 4; ++j) Ps[(fq * 4 + j) * 72 + sb * 16 + fr] = 0;
;           continue;
;         }
;     ...
; #pragma unroll
;       for (int ks = 0; ks < 2; ++ks) {
;         bf16x8 pf = *reinterpret_cast<const bf16x8*>(Ps + fr * 72 + ks * 32 + fq * 8);
; #pragma unroll
;         for (int dt = 0; dt < 8; ++dt) {
;           bf16x8 vf = *reinterpret_cast<const bf16x8*>(Vt + (dt * 16 + fr) * 72 + ks * 32 + fq * 8);
;           O[dt] = __builtin_amdgcn_mfma_f32_16x16x32_bf16(pf, vf, O[dt], 0, 0, 0);
;         }
;       }
.Latt_mask0:
	ds_write_b16 v97, v1 offset:35840
	ds_write_b16 v97, v1 offset:35984
	ds_write_b16 v97, v1 offset:36128
	ds_write_b16 v97, v1 offset:36272
.Latt_next0:
	s_waitcnt lgkmcnt(0)
	ds_read_b128 v[102:105], v90 offset:35840
	ds_read_b128 v[106:109], v90 offset:35904
	ds_read_b128 v[114:117], v95 offset:17408
	ds_read_b128 v[118:121], v95 offset:19712
	ds_read_b128 v[122:125], v95 offset:22016
	ds_read_b128 v[126:129], v95 offset:24320
	ds_read_b128 v[130:133], v95 offset:26624
	ds_read_b128 v[134:137], v95 offset:28928
	ds_read_b128 v[138:141], v95 offset:31232
	ds_read_b128 v[142:145], v95 offset:33536
	s_waitcnt lgkmcnt(7)
	v_mfma_f32_16x16x32_bf16 v[44:47], v[102:105], v[114:117], v[44:47]
	ds_read_b128 v[146:149], v95 offset:17472
	s_waitcnt lgkmcnt(7)
	v_mfma_f32_16x16x32_bf16 v[40:43], v[102:105], v[118:121], v[40:43]
	ds_read_b128 v[150:153], v95 offset:19776
	s_waitcnt lgkmcnt(7)
	v_mfma_f32_16x16x32_bf16 v[48:51], v[102:105], v[122:125], v[48:51]
	ds_read_b128 v[154:157], v95 offset:22080
	s_waitcnt lgkmcnt(7)
	v_mfma_f32_16x16x32_bf16 v[52:55], v[102:105], v[126:129], v[52:55]
	ds_read_b128 v[158:161], v95 offset:24384
	s_waitcnt lgkmcnt(7)
	v_mfma_f32_16x16x32_bf16 v[56:59], v[102:105], v[130:133], v[56:59]
	ds_read_b128 v[162:165], v95 offset:26688
	s_waitcnt lgkmcnt(7)
	v_mfma_f32_16x16x32_bf16 v[60:63], v[102:105], v[134:137], v[60:63]
	ds_read_b128 v[166:169], v95 offset:28992
	s_waitcnt lgkmcnt(7)
	v_mfma_f32_16x16x32_bf16 v[68:71], v[102:105], v[138:141], v[68:71]
	ds_read_b128 v[170:173], v95 offset:31296
	s_waitcnt lgkmcnt(7)
	v_mfma_f32_16x16x32_bf16 v[64:67], v[102:105], v[142:145], v[64:67]
	ds_read_b128 v[174:177], v95 offset:33600
	s_waitcnt lgkmcnt(7)
	v_mfma_f32_16x16x32_bf16 v[44:47], v[106:109], v[146:149], v[44:47]
	s_waitcnt lgkmcnt(6)
	v_mfma_f32_16x16x32_bf16 v[40:43], v[106:109], v[150:153], v[40:43]
	s_waitcnt lgkmcnt(5)
	v_mfma_f32_16x16x32_bf16 v[48:51], v[106:109], v[154:157], v[48:51]
	s_waitcnt lgkmcnt(4)
	v_mfma_f32_16x16x32_bf16 v[52:55], v[106:109], v[158:161], v[52:55]
	s_waitcnt lgkmcnt(3)
	v_mfma_f32_16x16x32_bf16 v[56:59], v[106:109], v[162:165], v[56:59]
	s_waitcnt lgkmcnt(2)
	v_mfma_f32_16x16x32_bf16 v[60:63], v[106:109], v[166:169], v[60:63]
	s_waitcnt lgkmcnt(1)
	v_mfma_f32_16x16x32_bf16 v[68:71], v[106:109], v[170:173], v[68:71]
	s_waitcnt lgkmcnt(0)
	v_mfma_f32_16x16x32_bf16 v[64:67], v[106:109], v[174:177], v[64:67]
